# PREP: one multiply feeds both exponentials (negated source modifier, same bits); dead accumulator clears removed from the merged stage
# speedup vs baseline: 1.0158x; 1.0041x over previous
.Lsx0_c:
	s_or_b64 exec, exec, s[2:3]
	s_and_saveexec_b64 s[2:3], s[56:57]
	s_cbranch_execz .LBB0_403
	ds_read_b128 v[48:51], v174
	ds_read_b128 v[60:63], v192 offset:49152
	ds_read_b128 v[52:55], v174 offset:64
	ds_read_b128 v[64:67], v192 offset:49216
	ds_read_b128 v[56:59], v175
	ds_read_b128 v[68:71], v199
	ds_read_b128 v[72:75], v192 offset:58368
	ds_read_b128 v[76:79], v192 offset:58432
	ds_read_b128 v[80:83], v151
	ds_read_b128 v[84:87], v151 offset:16
	ds_read_b128 v[88:91], v151 offset:32
	ds_read_b128 v[92:95], v151 offset:48
	s_waitcnt lgkmcnt(10)
	v_mfma_f32_16x16x32_bf16 v[30:33], v[48:51], v[60:63], 0
	s_waitcnt lgkmcnt(8)
	v_mfma_f32_16x16x32_bf16 v[30:33], v[52:55], v[64:67], v[30:33]
	s_waitcnt lgkmcnt(6)
	v_mfma_f32_16x16x32_bf16 v[30:33], v[56:59], v[68:71], v[30:33]
	s_waitcnt lgkmcnt(5)
	v_mfma_f32_16x16x32_bf16 v[22:25], v[48:51], v[72:75], 0
	s_waitcnt lgkmcnt(4)
	v_mfma_f32_16x16x32_bf16 v[22:25], v[52:55], v[76:79], v[22:25]
	s_cmp_eq_u32 s36, 0
	s_cbranch_scc1 .Lis0b
	s_cmp_gt_u32 s36, 62
	s_cbranch_scc1 .Lis0b
	s_add_i32 s24, s19, 0xffffffc0
	s_add_i32 s25, s21, 0x30
	s_and_b64 s[98:99], s[12:13], exec
	s_cselect_b32 s24, s25, s24
	v_lshl_add_u32 v194, s24, 6, v183
	v_lshlrev_b32_e32 v112, 1, v194
	global_load_dword v5, v112, s[44:45]
	global_load_dword v207, v112, s[44:45] offset:-1024
	global_load_dword v6, v112, s[42:43]
	global_load_dword v208, v112, s[42:43] offset:-1024
	global_load_dword v7, v112, s[0:1]
	global_load_dword v209, v112, s[0:1] offset:-1024
	global_load_dword v8, v112, s[34:35]
	global_load_dword v210, v112, s[34:35] offset:-1024
	global_load_dword v9, v112, s[76:77]
	global_load_dword v211, v112, s[76:77] offset:-1024
	v_add_u32_e32 v194, s24, v184
	v_lshlrev_b32_e32 v114, 2, v194
	global_load_dword v110, v114, s[40:41]
	global_load_dword v212, v114, s[40:41] offset:-32

.Lpq0_q0:
	ds_read2st64_b32 v[40:41], v143 offset0:96 offset1:97
	ds_read2st64_b32 v[42:43], v143 offset0:98 offset1:99
	ds_read2st64_b32 v[44:45], v143 offset0:100 offset1:101
	ds_read2st64_b32 v[46:47], v143 offset0:102 offset1:103
	ds_read2st64_b32 v[48:49], v143 offset0:104 offset1:105
	ds_read2st64_b32 v[50:51], v143 offset0:106 offset1:107
	ds_read2st64_b32 v[52:53], v143 offset0:108 offset1:109
	ds_read2st64_b32 v[54:55], v143 offset0:110 offset1:111
	ds_read2st64_b32 v[56:57], v143 offset0:112 offset1:113
	ds_read2st64_b32 v[58:59], v143 offset0:114 offset1:115
	ds_read2st64_b32 v[60:61], v143 offset0:116 offset1:117
	ds_read2st64_b32 v[62:63], v143 offset0:118 offset1:119
	v_lshrrev_b32_e32 v122, 1, v143
	v_mov_b32_e32 v69, 0
	s_waitcnt lgkmcnt(11)
	v_add_f32_e32 v65, v69, v41
	s_waitcnt lgkmcnt(8)
	v_add_f32_e32 v66, v65, v47
	s_waitcnt lgkmcnt(5)
	v_add_f32_e32 v67, v66, v53
	s_waitcnt lgkmcnt(2)
	v_add_f32_e32 v68, v67, v59
	v_mul_f32_e32 v79, 0xbfb8aa3b, v69
	v_exp_f32_e32 v70, v79
	v_mul_f32_e32 v80, 0x3fb8aa3b, v65
	v_exp_f32_e32 v75, v80
	v_exp_f32_e64 v71, -v80
	v_mul_f32_e32 v97, 0x3fb8aa3b, v66
	v_exp_f32_e32 v76, v97
	v_exp_f32_e64 v72, -v97
	v_mul_f32_e32 v80, 0x3fb8aa3b, v67
	v_exp_f32_e32 v77, v80
	v_exp_f32_e64 v73, -v80
	v_mul_f32_e32 v97, 0x3fb8aa3b, v68
	v_exp_f32_e32 v78, v97
	v_exp_f32_e64 v74, -v97
	s_nop 0
	v_mul_f32_e32 v81, v70, v40
	v_mul_f32_e32 v85, v75, v43
	v_mul_f32_e32 v89, v75, v42
	v_mul_f32_e32 v93, v71, v44
	v_mul_f32_e32 v82, v71, v46
	v_mul_f32_e32 v86, v76, v49
	v_mul_f32_e32 v90, v76, v48
	v_mul_f32_e32 v94, v72, v50
	v_mul_f32_e32 v83, v72, v52
	v_mul_f32_e32 v87, v77, v55
	v_mul_f32_e32 v91, v77, v54
	v_mul_f32_e32 v95, v73, v56
	v_mul_f32_e32 v84, v73, v58
	s_waitcnt lgkmcnt(1)
	v_mul_f32_e32 v88, v78, v61
	v_mul_f32_e32 v92, v78, v60
	s_waitcnt lgkmcnt(0)
	v_mul_f32_e32 v96, v74, v62
	v_cvt_pk_bf16_f32 v112, v81, v82
	v_cvt_pk_bf16_f32 v113, v83, v84
	v_cvt_pk_bf16_f32 v114, v85, v86
	v_cvt_pk_bf16_f32 v115, v87, v88
	v_cvt_pk_bf16_f32 v116, v89, v90
	v_cvt_pk_bf16_f32 v117, v91, v92
	v_cvt_pk_bf16_f32 v118, v93, v94
	v_cvt_pk_bf16_f32 v119, v95, v96
	v_cvt_pk_bf16_f32 v120, v45, v51
	v_cvt_pk_bf16_f32 v121, v57, v63
	ds_write_b16 v122, v112 offset:51456
	ds_write_b16_d16_hi v122, v112 offset:51600
	ds_write_b16 v122, v113 offset:51744
	ds_write_b16_d16_hi v122, v113 offset:51888
	ds_write_b16 v122, v114 offset:53760
	ds_write_b16_d16_hi v122, v114 offset:53904
	ds_write_b16 v122, v115 offset:54048
	ds_write_b16_d16_hi v122, v115 offset:54192
	ds_write_b16 v122, v116 offset:56064
	ds_write_b16_d16_hi v122, v116 offset:56208
	ds_write_b16 v122, v117 offset:56352
	ds_write_b16_d16_hi v122, v117 offset:56496
	ds_write_b16 v122, v118 offset:60672
	ds_write_b16_d16_hi v122, v118 offset:60816
	ds_write_b16 v122, v119 offset:60960
	ds_write_b16_d16_hi v122, v119 offset:61104
	ds_write_b64 v139, v[114:115] offset:5120
	ds_write_b64 v139, v[116:117] offset:5152
	ds_write_b64 v140, v[120:121] offset:5152
	s_branch .Lpq0_end
.Lpq0_q1:
	ds_read2st64_b32 v[26:27], v143 offset0:97 offset1:103
	ds_read2st64_b32 v[28:29], v143 offset0:109 offset1:115
	ds_read2st64_b32 v[40:41], v143 offset0:120 offset1:121
	ds_read2st64_b32 v[42:43], v143 offset0:122 offset1:123
	ds_read2st64_b32 v[44:45], v143 offset0:124 offset1:125
	ds_read2st64_b32 v[46:47], v143 offset0:126 offset1:127
	ds_read2st64_b32 v[48:49], v143 offset0:128 offset1:129
	ds_read2st64_b32 v[50:51], v143 offset0:130 offset1:131
	ds_read2st64_b32 v[52:53], v143 offset0:132 offset1:133
	ds_read2st64_b32 v[54:55], v143 offset0:134 offset1:135
	ds_read2st64_b32 v[56:57], v143 offset0:136 offset1:137
	ds_read2st64_b32 v[58:59], v143 offset0:138 offset1:139
	ds_read2st64_b32 v[60:61], v143 offset0:140 offset1:141
	ds_read2st64_b32 v[62:63], v143 offset0:142 offset1:143
	v_lshrrev_b32_e32 v122, 1, v143
	s_waitcnt lgkmcnt(13)
	v_add_f32_e32 v69, v26, v27
	s_waitcnt lgkmcnt(12)
	v_add_f32_e32 v69, v69, v28
	v_add_f32_e32 v69, v69, v29
	s_waitcnt lgkmcnt(11)
	v_add_f32_e32 v65, v69, v41
	s_waitcnt lgkmcnt(8)
	v_add_f32_e32 v66, v65, v47
	s_waitcnt lgkmcnt(5)
	v_add_f32_e32 v67, v66, v53
	s_waitcnt lgkmcnt(2)
	v_add_f32_e32 v68, v67, v59
	v_mul_f32_e32 v79, 0xbfb8aa3b, v69
	v_exp_f32_e32 v70, v79
	v_mul_f32_e32 v80, 0x3fb8aa3b, v65
	v_exp_f32_e32 v75, v80
	v_exp_f32_e64 v71, -v80
	v_mul_f32_e32 v97, 0x3fb8aa3b, v66
	v_exp_f32_e32 v76, v97
	v_exp_f32_e64 v72, -v97
	v_mul_f32_e32 v80, 0x3fb8aa3b, v67
	v_exp_f32_e32 v77, v80
	v_exp_f32_e64 v73, -v80
	v_mul_f32_e32 v97, 0x3fb8aa3b, v68
	v_exp_f32_e32 v78, v97
	v_exp_f32_e64 v74, -v97
	s_nop 0
	v_mul_f32_e32 v81, v70, v40
	v_mul_f32_e32 v85, v75, v43
	v_mul_f32_e32 v89, v75, v42
	v_mul_f32_e32 v93, v71, v44
	v_mul_f32_e32 v82, v71, v46
	v_mul_f32_e32 v86, v76, v49
	v_mul_f32_e32 v90, v76, v48
	v_mul_f32_e32 v94, v72, v50
	v_mul_f32_e32 v83, v72, v52
	v_mul_f32_e32 v87, v77, v55
	v_mul_f32_e32 v91, v77, v54
	v_mul_f32_e32 v95, v73, v56
	v_mul_f32_e32 v84, v73, v58
	s_waitcnt lgkmcnt(1)
	v_mul_f32_e32 v88, v78, v61
	v_mul_f32_e32 v92, v78, v60
	s_waitcnt lgkmcnt(0)
	v_mul_f32_e32 v96, v74, v62
	v_cvt_pk_bf16_f32 v112, v81, v82
	v_cvt_pk_bf16_f32 v113, v83, v84
	v_cvt_pk_bf16_f32 v114, v85, v86
	v_cvt_pk_bf16_f32 v115, v87, v88
	v_cvt_pk_bf16_f32 v116, v89, v90
	v_cvt_pk_bf16_f32 v117, v91, v92
	v_cvt_pk_bf16_f32 v118, v93, v94
	v_cvt_pk_bf16_f32 v119, v95, v96
	v_cvt_pk_bf16_f32 v120, v45, v51
	v_cvt_pk_bf16_f32 v121, v57, v63
	ds_write_b16 v122, v112 offset:52032
	ds_write_b16_d16_hi v122, v112 offset:52176
	ds_write_b16 v122, v113 offset:52320
	ds_write_b16_d16_hi v122, v113 offset:52464
	ds_write_b16 v122, v114 offset:54336
	ds_write_b16_d16_hi v122, v114 offset:54480
	ds_write_b16 v122, v115 offset:54624
	ds_write_b16_d16_hi v122, v115 offset:54768
	ds_write_b16 v122, v116 offset:56640
	ds_write_b16_d16_hi v122, v116 offset:56784
	ds_write_b16 v122, v117 offset:56928
	ds_write_b16_d16_hi v122, v117 offset:57072
	ds_write_b16 v122, v118 offset:61248
	ds_write_b16_d16_hi v122, v118 offset:61392
	ds_write_b16 v122, v119 offset:61536
	ds_write_b16_d16_hi v122, v119 offset:61680
	ds_write_b64 v139, v[114:115] offset:5128
	ds_write_b64 v139, v[116:117] offset:5160
	ds_write_b64 v140, v[120:121] offset:5160
	s_branch .Lpq0_end
.Lpq0_q2:
	ds_read2st64_b32 v[26:27], v143 offset0:97 offset1:103
	ds_read2st64_b32 v[28:29], v143 offset0:109 offset1:115
	ds_read2st64_b32 v[30:31], v143 offset0:121 offset1:127
	ds_read2st64_b32 v[32:33], v143 offset0:133 offset1:139
	ds_read2st64_b32 v[40:41], v143 offset0:144 offset1:145
	ds_read2st64_b32 v[42:43], v143 offset0:146 offset1:147
	ds_read2st64_b32 v[44:45], v143 offset0:148 offset1:149
	ds_read2st64_b32 v[46:47], v143 offset0:150 offset1:151
	ds_read2st64_b32 v[48:49], v143 offset0:152 offset1:153
	ds_read2st64_b32 v[50:51], v143 offset0:154 offset1:155
	ds_read2st64_b32 v[52:53], v143 offset0:156 offset1:157
	ds_read2st64_b32 v[54:55], v143 offset0:158 offset1:159
	ds_read2st64_b32 v[56:57], v143 offset0:160 offset1:161
	ds_read2st64_b32 v[58:59], v143 offset0:162 offset1:163
	ds_read2st64_b32 v[60:61], v143 offset0:164 offset1:165
	s_waitcnt lgkmcnt(14)
	ds_read2st64_b32 v[62:63], v143 offset0:166 offset1:167
	v_lshrrev_b32_e32 v122, 1, v143
	v_add_f32_e32 v69, v26, v27
	s_waitcnt lgkmcnt(14)
	v_add_f32_e32 v69, v69, v28
	v_add_f32_e32 v69, v69, v29
	s_waitcnt lgkmcnt(13)
	v_add_f32_e32 v69, v69, v30
	v_add_f32_e32 v69, v69, v31
	s_waitcnt lgkmcnt(12)
	v_add_f32_e32 v69, v69, v32
	v_add_f32_e32 v69, v69, v33
	s_waitcnt lgkmcnt(11)
	v_add_f32_e32 v65, v69, v41
	s_waitcnt lgkmcnt(8)
	v_add_f32_e32 v66, v65, v47
	s_waitcnt lgkmcnt(5)
	v_add_f32_e32 v67, v66, v53
	s_waitcnt lgkmcnt(2)
	v_add_f32_e32 v68, v67, v59
	v_mul_f32_e32 v79, 0xbfb8aa3b, v69
	v_exp_f32_e32 v70, v79
	v_mul_f32_e32 v80, 0x3fb8aa3b, v65
	v_exp_f32_e32 v75, v80
	v_exp_f32_e64 v71, -v80
	v_mul_f32_e32 v97, 0x3fb8aa3b, v66
	v_exp_f32_e32 v76, v97
	v_exp_f32_e64 v72, -v97
	v_mul_f32_e32 v80, 0x3fb8aa3b, v67
	v_exp_f32_e32 v77, v80
	v_exp_f32_e64 v73, -v80
	v_mul_f32_e32 v97, 0x3fb8aa3b, v68
	v_exp_f32_e32 v78, v97
	v_exp_f32_e64 v74, -v97
	s_nop 0
	v_mul_f32_e32 v81, v70, v40
	v_mul_f32_e32 v85, v75, v43
	v_mul_f32_e32 v89, v75, v42
	v_mul_f32_e32 v93, v71, v44
	v_mul_f32_e32 v82, v71, v46
	v_mul_f32_e32 v86, v76, v49
	v_mul_f32_e32 v90, v76, v48
	v_mul_f32_e32 v94, v72, v50
	v_mul_f32_e32 v83, v72, v52
	v_mul_f32_e32 v87, v77, v55
	v_mul_f32_e32 v91, v77, v54
	v_mul_f32_e32 v95, v73, v56
	v_mul_f32_e32 v84, v73, v58
	s_waitcnt lgkmcnt(1)
	v_mul_f32_e32 v88, v78, v61
	v_mul_f32_e32 v92, v78, v60
	s_waitcnt lgkmcnt(0)
	v_mul_f32_e32 v96, v74, v62
	v_cvt_pk_bf16_f32 v112, v81, v82
	v_cvt_pk_bf16_f32 v113, v83, v84
	v_cvt_pk_bf16_f32 v114, v85, v86
	v_cvt_pk_bf16_f32 v115, v87, v88
	v_cvt_pk_bf16_f32 v116, v89, v90
	v_cvt_pk_bf16_f32 v117, v91, v92
	v_cvt_pk_bf16_f32 v118, v93, v94
	v_cvt_pk_bf16_f32 v119, v95, v96
	v_cvt_pk_bf16_f32 v120, v45, v51
	v_cvt_pk_bf16_f32 v121, v57, v63
	ds_write_b16 v122, v112 offset:52608
	ds_write_b16_d16_hi v122, v112 offset:52752
	ds_write_b16 v122, v113 offset:52896
	ds_write_b16_d16_hi v122, v113 offset:53040
	ds_write_b16 v122, v114 offset:54912
	ds_write_b16_d16_hi v122, v114 offset:55056
	ds_write_b16 v122, v115 offset:55200
	ds_write_b16_d16_hi v122, v115 offset:55344
	ds_write_b16 v122, v116 offset:57216
	ds_write_b16_d16_hi v122, v116 offset:57360
	ds_write_b16 v122, v117 offset:57504
	ds_write_b16_d16_hi v122, v117 offset:57648
	ds_write_b16 v122, v118 offset:61824
	ds_write_b16_d16_hi v122, v118 offset:61968
	ds_write_b16 v122, v119 offset:62112
	ds_write_b16_d16_hi v122, v119 offset:62256
	ds_write_b64 v139, v[114:115] offset:5136
	ds_write_b64 v139, v[116:117] offset:5168
	ds_write_b64 v140, v[120:121] offset:5168
	s_branch .Lpq0_end
.Lpq0_q3:
	ds_read2st64_b32 v[26:27], v143 offset0:97 offset1:103
	ds_read2st64_b32 v[28:29], v143 offset0:109 offset1:115
	ds_read2st64_b32 v[30:31], v143 offset0:121 offset1:127
	ds_read2st64_b32 v[32:33], v143 offset0:133 offset1:139
	ds_read2st64_b32 v[34:35], v143 offset0:145 offset1:151
	ds_read2st64_b32 v[36:37], v143 offset0:157 offset1:163
	ds_read2st64_b32 v[40:41], v143 offset0:168 offset1:169
	ds_read2st64_b32 v[42:43], v143 offset0:170 offset1:171
	ds_read2st64_b32 v[44:45], v143 offset0:172 offset1:173
	ds_read2st64_b32 v[46:47], v143 offset0:174 offset1:175
	ds_read2st64_b32 v[48:49], v143 offset0:176 offset1:177
	ds_read2st64_b32 v[50:51], v143 offset0:178 offset1:179
	ds_read2st64_b32 v[52:53], v143 offset0:180 offset1:181
	ds_read2st64_b32 v[54:55], v143 offset0:182 offset1:183
	ds_read2st64_b32 v[56:57], v143 offset0:184 offset1:185
	s_waitcnt lgkmcnt(14)
	ds_read2st64_b32 v[58:59], v143 offset0:186 offset1:187
	s_waitcnt lgkmcnt(14)
	ds_read2st64_b32 v[60:61], v143 offset0:188 offset1:189
	s_waitcnt lgkmcnt(14)
	ds_read2st64_b32 v[62:63], v143 offset0:190 offset1:191
	v_lshrrev_b32_e32 v122, 1, v143
	v_add_f32_e32 v69, v26, v27
	v_add_f32_e32 v69, v69, v28
	v_add_f32_e32 v69, v69, v29
	v_add_f32_e32 v69, v69, v30
	v_add_f32_e32 v69, v69, v31
	s_waitcnt lgkmcnt(14)
	v_add_f32_e32 v69, v69, v32
	v_add_f32_e32 v69, v69, v33
	s_waitcnt lgkmcnt(13)
	v_add_f32_e32 v69, v69, v34
	v_add_f32_e32 v69, v69, v35
	s_waitcnt lgkmcnt(12)
	v_add_f32_e32 v69, v69, v36
	v_add_f32_e32 v69, v69, v37
	s_waitcnt lgkmcnt(11)
	v_add_f32_e32 v65, v69, v41
	s_waitcnt lgkmcnt(8)
	v_add_f32_e32 v66, v65, v47
	s_waitcnt lgkmcnt(5)
	v_add_f32_e32 v67, v66, v53
	s_waitcnt lgkmcnt(2)
	v_add_f32_e32 v68, v67, v59
	v_mul_f32_e32 v79, 0xbfb8aa3b, v69
	v_exp_f32_e32 v70, v79
	v_mul_f32_e32 v80, 0x3fb8aa3b, v65
	v_exp_f32_e32 v75, v80
	v_exp_f32_e64 v71, -v80
	v_mul_f32_e32 v97, 0x3fb8aa3b, v66
	v_exp_f32_e32 v76, v97
	v_exp_f32_e64 v72, -v97
	v_mul_f32_e32 v80, 0x3fb8aa3b, v67
	v_exp_f32_e32 v77, v80
	v_exp_f32_e64 v73, -v80
	v_mul_f32_e32 v97, 0x3fb8aa3b, v68
	v_exp_f32_e32 v78, v97
	v_exp_f32_e64 v74, -v97
	s_nop 0
	v_mul_f32_e32 v81, v70, v40
	v_mul_f32_e32 v85, v75, v43
	v_mul_f32_e32 v89, v75, v42
	v_mul_f32_e32 v93, v71, v44
	v_mul_f32_e32 v82, v71, v46
	v_mul_f32_e32 v86, v76, v49
	v_mul_f32_e32 v90, v76, v48
	v_mul_f32_e32 v94, v72, v50
	v_mul_f32_e32 v83, v72, v52
	v_mul_f32_e32 v87, v77, v55
	v_mul_f32_e32 v91, v77, v54
	v_mul_f32_e32 v95, v73, v56
	v_mul_f32_e32 v84, v73, v58
	s_waitcnt lgkmcnt(1)
	v_mul_f32_e32 v88, v78, v61
	v_mul_f32_e32 v92, v78, v60
	s_waitcnt lgkmcnt(0)
	v_mul_f32_e32 v96, v74, v62
	v_cvt_pk_bf16_f32 v112, v81, v82
	v_cvt_pk_bf16_f32 v113, v83, v84
	v_cvt_pk_bf16_f32 v114, v85, v86
	v_cvt_pk_bf16_f32 v115, v87, v88
	v_cvt_pk_bf16_f32 v116, v89, v90
	v_cvt_pk_bf16_f32 v117, v91, v92
	v_cvt_pk_bf16_f32 v118, v93, v94
	v_cvt_pk_bf16_f32 v119, v95, v96
	v_cvt_pk_bf16_f32 v120, v45, v51
	v_cvt_pk_bf16_f32 v121, v57, v63
	ds_write_b16 v122, v112 offset:53184
	ds_write_b16_d16_hi v122, v112 offset:53328
	ds_write_b16 v122, v113 offset:53472
	ds_write_b16_d16_hi v122, v113 offset:53616
	ds_write_b16 v122, v114 offset:55488
	ds_write_b16_d16_hi v122, v114 offset:55632
	ds_write_b16 v122, v115 offset:55776
	ds_write_b16_d16_hi v122, v115 offset:55920
	ds_write_b16 v122, v116 offset:57792
	ds_write_b16_d16_hi v122, v116 offset:57936
	ds_write_b16 v122, v117 offset:58080
	ds_write_b16_d16_hi v122, v117 offset:58224
	ds_write_b16 v122, v118 offset:62400
	ds_write_b16_d16_hi v122, v118 offset:62544
	ds_write_b16 v122, v119 offset:62688
	ds_write_b16_d16_hi v122, v119 offset:62832
	ds_write_b64 v139, v[114:115] offset:5144
	ds_write_b64 v139, v[116:117] offset:5176
	ds_write_b64 v140, v[120:121] offset:5176
	v_add_u32_e32 v123, 0x18e00, v143
	ds_write_b32 v123, v74
	s_branch .Lpq0_end

.Lsx1_c:
	s_or_b64 exec, exec, s[74:75]
	s_and_saveexec_b64 s[74:75], s[56:57]
	s_cbranch_execz .LBB0_432
	ds_read_b128 v[48:51], v174
	ds_read_b128 v[60:63], v192 offset:51456
	ds_read_b128 v[52:55], v174 offset:64
	ds_read_b128 v[64:67], v192 offset:51520
	ds_read_b128 v[56:59], v175 offset:5120
	ds_read_b128 v[68:71], v199
	ds_read_b128 v[72:75], v192 offset:60672
	ds_read_b128 v[76:79], v192 offset:60736
	ds_read_b128 v[80:83], v151
	ds_read_b128 v[84:87], v151 offset:16
	ds_read_b128 v[88:91], v151 offset:32
	ds_read_b128 v[92:95], v151 offset:48
	s_waitcnt lgkmcnt(10)
	v_mfma_f32_16x16x32_bf16 v[30:33], v[48:51], v[60:63], 0
	s_waitcnt lgkmcnt(8)
	v_mfma_f32_16x16x32_bf16 v[30:33], v[52:55], v[64:67], v[30:33]
	s_waitcnt lgkmcnt(6)
	v_mfma_f32_16x16x32_bf16 v[30:33], v[56:59], v[68:71], v[30:33]
	s_waitcnt lgkmcnt(5)
	v_mfma_f32_16x16x32_bf16 v[22:25], v[48:51], v[72:75], 0
	s_waitcnt lgkmcnt(4)
	v_mfma_f32_16x16x32_bf16 v[22:25], v[52:55], v[76:79], v[22:25]
	s_cmp_gt_u32 s36, 61
	s_cbranch_scc1 .Lis1bw
	s_add_i32 s24, s19, 0xffffffb0
	s_add_i32 s25, s21, 64
	s_and_b64 s[98:99], s[12:13], exec
	s_cselect_b32 s24, s25, s24
	v_lshl_add_u32 v194, s24, 6, v183
	v_lshlrev_b32_e32 v112, 1, v194
	global_load_dword v0, v112, s[44:45]
	global_load_dword v201, v112, s[44:45] offset:-1024
	global_load_dword v1, v112, s[42:43]
	global_load_dword v202, v112, s[42:43] offset:-1024
	global_load_dword v2, v112, s[0:1]
	global_load_dword v203, v112, s[0:1] offset:-1024
	global_load_dword v4, v112, s[76:77]
	global_load_dword v205, v112, s[76:77] offset:-1024
	global_load_dword v3, v112, s[34:35]
	global_load_dword v204, v112, s[34:35] offset:-1024
	v_add_u32_e32 v194, s24, v184
	v_lshlrev_b32_e32 v114, 2, v194
	global_load_dword v108, v114, s[40:41]
	global_load_dword v206, v114, s[40:41] offset:-32
	s_branch .Lis1b

.Lpq1_q0:
	ds_read2st64_b32 v[40:41], v143 offset0:0 offset1:1
	ds_read2st64_b32 v[42:43], v143 offset0:2 offset1:3
	ds_read2st64_b32 v[44:45], v143 offset0:4 offset1:5
	ds_read2st64_b32 v[46:47], v143 offset0:6 offset1:7
	ds_read2st64_b32 v[48:49], v143 offset0:8 offset1:9
	ds_read2st64_b32 v[50:51], v143 offset0:10 offset1:11
	ds_read2st64_b32 v[52:53], v143 offset0:12 offset1:13
	ds_read2st64_b32 v[54:55], v143 offset0:14 offset1:15
	ds_read2st64_b32 v[56:57], v143 offset0:16 offset1:17
	ds_read2st64_b32 v[58:59], v143 offset0:18 offset1:19
	ds_read2st64_b32 v[60:61], v143 offset0:20 offset1:21
	ds_read2st64_b32 v[62:63], v143 offset0:22 offset1:23
	v_lshrrev_b32_e32 v122, 1, v143
	v_mov_b32_e32 v69, 0
	s_waitcnt lgkmcnt(11)
	v_add_f32_e32 v65, v69, v41
	s_waitcnt lgkmcnt(8)
	v_add_f32_e32 v66, v65, v47
	s_waitcnt lgkmcnt(5)
	v_add_f32_e32 v67, v66, v53
	s_waitcnt lgkmcnt(2)
	v_add_f32_e32 v68, v67, v59
	v_mul_f32_e32 v79, 0xbfb8aa3b, v69
	v_exp_f32_e32 v70, v79
	v_mul_f32_e32 v80, 0x3fb8aa3b, v65
	v_exp_f32_e32 v75, v80
	v_exp_f32_e64 v71, -v80
	v_mul_f32_e32 v97, 0x3fb8aa3b, v66
	v_exp_f32_e32 v76, v97
	v_exp_f32_e64 v72, -v97
	v_mul_f32_e32 v80, 0x3fb8aa3b, v67
	v_exp_f32_e32 v77, v80
	v_exp_f32_e64 v73, -v80
	v_mul_f32_e32 v97, 0x3fb8aa3b, v68
	v_exp_f32_e32 v78, v97
	v_exp_f32_e64 v74, -v97
	s_nop 0
	v_mul_f32_e32 v81, v70, v40
	v_mul_f32_e32 v85, v75, v43
	v_mul_f32_e32 v89, v75, v42
	v_mul_f32_e32 v93, v71, v44
	v_mul_f32_e32 v82, v71, v46
	v_mul_f32_e32 v86, v76, v49
	v_mul_f32_e32 v90, v76, v48
	v_mul_f32_e32 v94, v72, v50
	v_mul_f32_e32 v83, v72, v52
	v_mul_f32_e32 v87, v77, v55
	v_mul_f32_e32 v91, v77, v54
	v_mul_f32_e32 v95, v73, v56
	v_mul_f32_e32 v84, v73, v58
	s_waitcnt lgkmcnt(1)
	v_mul_f32_e32 v88, v78, v61
	v_mul_f32_e32 v92, v78, v60
	s_waitcnt lgkmcnt(0)
	v_mul_f32_e32 v96, v74, v62
	v_cvt_pk_bf16_f32 v112, v81, v82
	v_cvt_pk_bf16_f32 v113, v83, v84
	v_cvt_pk_bf16_f32 v114, v85, v86
	v_cvt_pk_bf16_f32 v115, v87, v88
	v_cvt_pk_bf16_f32 v116, v89, v90
	v_cvt_pk_bf16_f32 v117, v91, v92
	v_cvt_pk_bf16_f32 v118, v93, v94
	v_cvt_pk_bf16_f32 v119, v95, v96
	v_cvt_pk_bf16_f32 v120, v45, v51
	v_cvt_pk_bf16_f32 v121, v57, v63
	ds_write_b16 v122, v112 offset:49152
	ds_write_b16_d16_hi v122, v112 offset:49296
	ds_write_b16 v122, v113 offset:49440
	ds_write_b16_d16_hi v122, v113 offset:49584
	ds_write_b16 v122, v114 offset:53760
	ds_write_b16_d16_hi v122, v114 offset:53904
	ds_write_b16 v122, v115 offset:54048
	ds_write_b16_d16_hi v122, v115 offset:54192
	ds_write_b16 v122, v116 offset:56064
	ds_write_b16_d16_hi v122, v116 offset:56208
	ds_write_b16 v122, v117 offset:56352
	ds_write_b16_d16_hi v122, v117 offset:56496
	ds_write_b16 v122, v118 offset:58368
	ds_write_b16_d16_hi v122, v118 offset:58512
	ds_write_b16 v122, v119 offset:58656
	ds_write_b16_d16_hi v122, v119 offset:58800
	ds_write_b64 v139, v[114:115] offset:0
	ds_write_b64 v139, v[116:117] offset:32
	ds_write_b64 v140, v[120:121] offset:32
	s_branch .Lpq1_end
.Lpq1_q1:
	ds_read2st64_b32 v[26:27], v143 offset0:1 offset1:7
	ds_read2st64_b32 v[28:29], v143 offset0:13 offset1:19
	ds_read2st64_b32 v[40:41], v143 offset0:24 offset1:25
	ds_read2st64_b32 v[42:43], v143 offset0:26 offset1:27
	ds_read2st64_b32 v[44:45], v143 offset0:28 offset1:29
	ds_read2st64_b32 v[46:47], v143 offset0:30 offset1:31
	ds_read2st64_b32 v[48:49], v143 offset0:32 offset1:33
	ds_read2st64_b32 v[50:51], v143 offset0:34 offset1:35
	ds_read2st64_b32 v[52:53], v143 offset0:36 offset1:37
	ds_read2st64_b32 v[54:55], v143 offset0:38 offset1:39
	ds_read2st64_b32 v[56:57], v143 offset0:40 offset1:41
	ds_read2st64_b32 v[58:59], v143 offset0:42 offset1:43
	ds_read2st64_b32 v[60:61], v143 offset0:44 offset1:45
	ds_read2st64_b32 v[62:63], v143 offset0:46 offset1:47
	v_lshrrev_b32_e32 v122, 1, v143
	s_waitcnt lgkmcnt(13)
	v_add_f32_e32 v69, v26, v27
	s_waitcnt lgkmcnt(12)
	v_add_f32_e32 v69, v69, v28
	v_add_f32_e32 v69, v69, v29
	s_waitcnt lgkmcnt(11)
	v_add_f32_e32 v65, v69, v41
	s_waitcnt lgkmcnt(8)
	v_add_f32_e32 v66, v65, v47
	s_waitcnt lgkmcnt(5)
	v_add_f32_e32 v67, v66, v53
	s_waitcnt lgkmcnt(2)
	v_add_f32_e32 v68, v67, v59
	v_mul_f32_e32 v79, 0xbfb8aa3b, v69
	v_exp_f32_e32 v70, v79
	v_mul_f32_e32 v80, 0x3fb8aa3b, v65
	v_exp_f32_e32 v75, v80
	v_exp_f32_e64 v71, -v80
	v_mul_f32_e32 v97, 0x3fb8aa3b, v66
	v_exp_f32_e32 v76, v97
	v_exp_f32_e64 v72, -v97
	v_mul_f32_e32 v80, 0x3fb8aa3b, v67
	v_exp_f32_e32 v77, v80
	v_exp_f32_e64 v73, -v80
	v_mul_f32_e32 v97, 0x3fb8aa3b, v68
	v_exp_f32_e32 v78, v97
	v_exp_f32_e64 v74, -v97
	s_nop 0
	v_mul_f32_e32 v81, v70, v40
	v_mul_f32_e32 v85, v75, v43
	v_mul_f32_e32 v89, v75, v42
	v_mul_f32_e32 v93, v71, v44
	v_mul_f32_e32 v82, v71, v46
	v_mul_f32_e32 v86, v76, v49
	v_mul_f32_e32 v90, v76, v48
	v_mul_f32_e32 v94, v72, v50
	v_mul_f32_e32 v83, v72, v52
	v_mul_f32_e32 v87, v77, v55
	v_mul_f32_e32 v91, v77, v54
	v_mul_f32_e32 v95, v73, v56
	v_mul_f32_e32 v84, v73, v58
	s_waitcnt lgkmcnt(1)
	v_mul_f32_e32 v88, v78, v61
	v_mul_f32_e32 v92, v78, v60
	s_waitcnt lgkmcnt(0)
	v_mul_f32_e32 v96, v74, v62
	v_cvt_pk_bf16_f32 v112, v81, v82
	v_cvt_pk_bf16_f32 v113, v83, v84
	v_cvt_pk_bf16_f32 v114, v85, v86
	v_cvt_pk_bf16_f32 v115, v87, v88
	v_cvt_pk_bf16_f32 v116, v89, v90
	v_cvt_pk_bf16_f32 v117, v91, v92
	v_cvt_pk_bf16_f32 v118, v93, v94
	v_cvt_pk_bf16_f32 v119, v95, v96
	v_cvt_pk_bf16_f32 v120, v45, v51
	v_cvt_pk_bf16_f32 v121, v57, v63
	ds_write_b16 v122, v112 offset:49728
	ds_write_b16_d16_hi v122, v112 offset:49872
	ds_write_b16 v122, v113 offset:50016
	ds_write_b16_d16_hi v122, v113 offset:50160
	ds_write_b16 v122, v114 offset:54336
	ds_write_b16_d16_hi v122, v114 offset:54480
	ds_write_b16 v122, v115 offset:54624
	ds_write_b16_d16_hi v122, v115 offset:54768
	ds_write_b16 v122, v116 offset:56640
	ds_write_b16_d16_hi v122, v116 offset:56784
	ds_write_b16 v122, v117 offset:56928
	ds_write_b16_d16_hi v122, v117 offset:57072
	ds_write_b16 v122, v118 offset:58944
	ds_write_b16_d16_hi v122, v118 offset:59088
	ds_write_b16 v122, v119 offset:59232
	ds_write_b16_d16_hi v122, v119 offset:59376
	ds_write_b64 v139, v[114:115] offset:8
	ds_write_b64 v139, v[116:117] offset:40
	ds_write_b64 v140, v[120:121] offset:40
	s_branch .Lpq1_end
.Lpq1_q2:
	ds_read2st64_b32 v[26:27], v143 offset0:1 offset1:7
	ds_read2st64_b32 v[28:29], v143 offset0:13 offset1:19
	ds_read2st64_b32 v[30:31], v143 offset0:25 offset1:31
	ds_read2st64_b32 v[32:33], v143 offset0:37 offset1:43
	ds_read2st64_b32 v[40:41], v143 offset0:48 offset1:49
	ds_read2st64_b32 v[42:43], v143 offset0:50 offset1:51
	ds_read2st64_b32 v[44:45], v143 offset0:52 offset1:53
	ds_read2st64_b32 v[46:47], v143 offset0:54 offset1:55
	ds_read2st64_b32 v[48:49], v143 offset0:56 offset1:57
	ds_read2st64_b32 v[50:51], v143 offset0:58 offset1:59
	ds_read2st64_b32 v[52:53], v143 offset0:60 offset1:61
	ds_read2st64_b32 v[54:55], v143 offset0:62 offset1:63
	ds_read2st64_b32 v[56:57], v143 offset0:64 offset1:65
	ds_read2st64_b32 v[58:59], v143 offset0:66 offset1:67
	ds_read2st64_b32 v[60:61], v143 offset0:68 offset1:69
	s_waitcnt lgkmcnt(14)
	ds_read2st64_b32 v[62:63], v143 offset0:70 offset1:71
	v_lshrrev_b32_e32 v122, 1, v143
	v_add_f32_e32 v69, v26, v27
	s_waitcnt lgkmcnt(14)
	v_add_f32_e32 v69, v69, v28
	v_add_f32_e32 v69, v69, v29
	s_waitcnt lgkmcnt(13)
	v_add_f32_e32 v69, v69, v30
	v_add_f32_e32 v69, v69, v31
	s_waitcnt lgkmcnt(12)
	v_add_f32_e32 v69, v69, v32
	v_add_f32_e32 v69, v69, v33
	s_waitcnt lgkmcnt(11)
	v_add_f32_e32 v65, v69, v41
	s_waitcnt lgkmcnt(8)
	v_add_f32_e32 v66, v65, v47
	s_waitcnt lgkmcnt(5)
	v_add_f32_e32 v67, v66, v53
	s_waitcnt lgkmcnt(2)
	v_add_f32_e32 v68, v67, v59
	v_mul_f32_e32 v79, 0xbfb8aa3b, v69
	v_exp_f32_e32 v70, v79
	v_mul_f32_e32 v80, 0x3fb8aa3b, v65
	v_exp_f32_e32 v75, v80
	v_exp_f32_e64 v71, -v80
	v_mul_f32_e32 v97, 0x3fb8aa3b, v66
	v_exp_f32_e32 v76, v97
	v_exp_f32_e64 v72, -v97
	v_mul_f32_e32 v80, 0x3fb8aa3b, v67
	v_exp_f32_e32 v77, v80
	v_exp_f32_e64 v73, -v80
	v_mul_f32_e32 v97, 0x3fb8aa3b, v68
	v_exp_f32_e32 v78, v97
	v_exp_f32_e64 v74, -v97
	s_nop 0
	v_mul_f32_e32 v81, v70, v40
	v_mul_f32_e32 v85, v75, v43
	v_mul_f32_e32 v89, v75, v42
	v_mul_f32_e32 v93, v71, v44
	v_mul_f32_e32 v82, v71, v46
	v_mul_f32_e32 v86, v76, v49
	v_mul_f32_e32 v90, v76, v48
	v_mul_f32_e32 v94, v72, v50
	v_mul_f32_e32 v83, v72, v52
	v_mul_f32_e32 v87, v77, v55
	v_mul_f32_e32 v91, v77, v54
	v_mul_f32_e32 v95, v73, v56
	v_mul_f32_e32 v84, v73, v58
	s_waitcnt lgkmcnt(1)
	v_mul_f32_e32 v88, v78, v61
	v_mul_f32_e32 v92, v78, v60
	s_waitcnt lgkmcnt(0)
	v_mul_f32_e32 v96, v74, v62
	v_cvt_pk_bf16_f32 v112, v81, v82
	v_cvt_pk_bf16_f32 v113, v83, v84
	v_cvt_pk_bf16_f32 v114, v85, v86
	v_cvt_pk_bf16_f32 v115, v87, v88
	v_cvt_pk_bf16_f32 v116, v89, v90
	v_cvt_pk_bf16_f32 v117, v91, v92
	v_cvt_pk_bf16_f32 v118, v93, v94
	v_cvt_pk_bf16_f32 v119, v95, v96
	v_cvt_pk_bf16_f32 v120, v45, v51
	v_cvt_pk_bf16_f32 v121, v57, v63
	ds_write_b16 v122, v112 offset:50304
	ds_write_b16_d16_hi v122, v112 offset:50448
	ds_write_b16 v122, v113 offset:50592
	ds_write_b16_d16_hi v122, v113 offset:50736
	ds_write_b16 v122, v114 offset:54912
	ds_write_b16_d16_hi v122, v114 offset:55056
	ds_write_b16 v122, v115 offset:55200
	ds_write_b16_d16_hi v122, v115 offset:55344
	ds_write_b16 v122, v116 offset:57216
	ds_write_b16_d16_hi v122, v116 offset:57360
	ds_write_b16 v122, v117 offset:57504
	ds_write_b16_d16_hi v122, v117 offset:57648
	ds_write_b16 v122, v118 offset:59520
	ds_write_b16_d16_hi v122, v118 offset:59664
	ds_write_b16 v122, v119 offset:59808
	ds_write_b16_d16_hi v122, v119 offset:59952
	ds_write_b64 v139, v[114:115] offset:16
	ds_write_b64 v139, v[116:117] offset:48
	ds_write_b64 v140, v[120:121] offset:48
	s_branch .Lpq1_end
.Lpq1_q3:
	ds_read2st64_b32 v[26:27], v143 offset0:1 offset1:7
	ds_read2st64_b32 v[28:29], v143 offset0:13 offset1:19
	ds_read2st64_b32 v[30:31], v143 offset0:25 offset1:31
	ds_read2st64_b32 v[32:33], v143 offset0:37 offset1:43
	ds_read2st64_b32 v[34:35], v143 offset0:49 offset1:55
	ds_read2st64_b32 v[36:37], v143 offset0:61 offset1:67
	ds_read2st64_b32 v[40:41], v143 offset0:72 offset1:73
	ds_read2st64_b32 v[42:43], v143 offset0:74 offset1:75
	ds_read2st64_b32 v[44:45], v143 offset0:76 offset1:77
	ds_read2st64_b32 v[46:47], v143 offset0:78 offset1:79
	ds_read2st64_b32 v[48:49], v143 offset0:80 offset1:81
	ds_read2st64_b32 v[50:51], v143 offset0:82 offset1:83
	ds_read2st64_b32 v[52:53], v143 offset0:84 offset1:85
	ds_read2st64_b32 v[54:55], v143 offset0:86 offset1:87
	ds_read2st64_b32 v[56:57], v143 offset0:88 offset1:89
	s_waitcnt lgkmcnt(14)
	ds_read2st64_b32 v[58:59], v143 offset0:90 offset1:91
	s_waitcnt lgkmcnt(14)
	ds_read2st64_b32 v[60:61], v143 offset0:92 offset1:93
	s_waitcnt lgkmcnt(14)
	ds_read2st64_b32 v[62:63], v143 offset0:94 offset1:95
	v_lshrrev_b32_e32 v122, 1, v143
	v_add_f32_e32 v69, v26, v27
	v_add_f32_e32 v69, v69, v28
	v_add_f32_e32 v69, v69, v29
	v_add_f32_e32 v69, v69, v30
	v_add_f32_e32 v69, v69, v31
	s_waitcnt lgkmcnt(14)
	v_add_f32_e32 v69, v69, v32
	v_add_f32_e32 v69, v69, v33
	s_waitcnt lgkmcnt(13)
	v_add_f32_e32 v69, v69, v34
	v_add_f32_e32 v69, v69, v35
	s_waitcnt lgkmcnt(12)
	v_add_f32_e32 v69, v69, v36
	v_add_f32_e32 v69, v69, v37
	s_waitcnt lgkmcnt(11)
	v_add_f32_e32 v65, v69, v41
	s_waitcnt lgkmcnt(8)
	v_add_f32_e32 v66, v65, v47
	s_waitcnt lgkmcnt(5)
	v_add_f32_e32 v67, v66, v53
	s_waitcnt lgkmcnt(2)
	v_add_f32_e32 v68, v67, v59
	v_mul_f32_e32 v79, 0xbfb8aa3b, v69
	v_exp_f32_e32 v70, v79
	v_mul_f32_e32 v80, 0x3fb8aa3b, v65
	v_exp_f32_e32 v75, v80
	v_exp_f32_e64 v71, -v80
	v_mul_f32_e32 v97, 0x3fb8aa3b, v66
	v_exp_f32_e32 v76, v97
	v_exp_f32_e64 v72, -v97
	v_mul_f32_e32 v80, 0x3fb8aa3b, v67
	v_exp_f32_e32 v77, v80
	v_exp_f32_e64 v73, -v80
	v_mul_f32_e32 v97, 0x3fb8aa3b, v68
	v_exp_f32_e32 v78, v97
	v_exp_f32_e64 v74, -v97
	s_nop 0
	v_mul_f32_e32 v81, v70, v40
	v_mul_f32_e32 v85, v75, v43
	v_mul_f32_e32 v89, v75, v42
	v_mul_f32_e32 v93, v71, v44
	v_mul_f32_e32 v82, v71, v46
	v_mul_f32_e32 v86, v76, v49
	v_mul_f32_e32 v90, v76, v48
	v_mul_f32_e32 v94, v72, v50
	v_mul_f32_e32 v83, v72, v52
	v_mul_f32_e32 v87, v77, v55
	v_mul_f32_e32 v91, v77, v54
	v_mul_f32_e32 v95, v73, v56
	v_mul_f32_e32 v84, v73, v58
	s_waitcnt lgkmcnt(1)
	v_mul_f32_e32 v88, v78, v61
	v_mul_f32_e32 v92, v78, v60
	s_waitcnt lgkmcnt(0)
	v_mul_f32_e32 v96, v74, v62
	v_cvt_pk_bf16_f32 v112, v81, v82
	v_cvt_pk_bf16_f32 v113, v83, v84
	v_cvt_pk_bf16_f32 v114, v85, v86
	v_cvt_pk_bf16_f32 v115, v87, v88
	v_cvt_pk_bf16_f32 v116, v89, v90
	v_cvt_pk_bf16_f32 v117, v91, v92
	v_cvt_pk_bf16_f32 v118, v93, v94
	v_cvt_pk_bf16_f32 v119, v95, v96
	v_cvt_pk_bf16_f32 v120, v45, v51
	v_cvt_pk_bf16_f32 v121, v57, v63
	ds_write_b16 v122, v112 offset:50880
	ds_write_b16_d16_hi v122, v112 offset:51024
	ds_write_b16 v122, v113 offset:51168
	ds_write_b16_d16_hi v122, v113 offset:51312
	ds_write_b16 v122, v114 offset:55488
	ds_write_b16_d16_hi v122, v114 offset:55632
	ds_write_b16 v122, v115 offset:55776
	ds_write_b16_d16_hi v122, v115 offset:55920
	ds_write_b16 v122, v116 offset:57792
	ds_write_b16_d16_hi v122, v116 offset:57936
	ds_write_b16 v122, v117 offset:58080
	ds_write_b16_d16_hi v122, v117 offset:58224
	ds_write_b16 v122, v118 offset:60096
	ds_write_b16_d16_hi v122, v118 offset:60240
	ds_write_b16 v122, v119 offset:60384
	ds_write_b16_d16_hi v122, v119 offset:60528
	ds_write_b64 v139, v[114:115] offset:24
	ds_write_b64 v139, v[116:117] offset:56
	ds_write_b64 v140, v[120:121] offset:56
	v_add_u32_e32 v123, 0x18d00, v143
	ds_write_b32 v123, v74
	s_branch .Lpq1_end
